# p4 retention GroupNorm: 16-lane row reductions done with DPP adds (quad_perm, row_half_mirror, row_mirror) instead of 32 serialized ds_bpermute round trips per item; bit-identical
# speedup vs baseline: 1.0110x; 1.0110x over previous
.LBB0_393:
	ds_read_b128 v[242:245], v223
	ds_read_b128 v[246:249], v224
	v_mul_f32_e32 v235, v143, v217
	v_exp_f32_e32 v237, v235
	v_mul_f32_e32 v235, v143, v218
	s_waitcnt lgkmcnt(1)
	v_mfma_f32_16x16x32_bf16 v[242:245], v[84:87], v[242:245], 0
	v_exp_f32_e32 v238, v235
	v_mul_f32_e32 v235, v143, v219
	v_mul_f32_e32 v143, v143, v220
	s_waitcnt lgkmcnt(0)
	v_mfma_f32_16x16x32_bf16 v[242:245], v[92:95], v[246:249], v[242:245]
	ds_read_b128 v[246:249], v225
	v_exp_f32_e32 v239, v235
	v_exp_f32_e32 v240, v143
	v_readlane_b32 s72, v251, 8
	s_waitcnt lgkmcnt(0)
	v_mfma_f32_16x16x32_bf16 v[242:245], v[80:83], v[246:249], v[242:245]
	ds_read_b128 v[246:249], v226
	v_readlane_b32 s76, v251, 12
	v_readlane_b32 s77, v251, 13
	s_waitcnt lgkmcnt(0)
	v_mfma_f32_16x16x32_bf16 v[242:245], v[88:91], v[246:249], v[242:245]
	s_lshl_b32 s46, s41, 8
	ds_read_b128 v[246:249], v224 offset:4096
	s_mov_b64 s[16:17], 0xe200800
	s_nop 4
	v_fma_f32 v235, v237, v242, v116
	v_fma_f32 v143, v238, v243, v117
	v_fma_f32 v116, v239, v244, v118
	v_fmac_f32_e32 v119, v240, v245
	ds_read_b128 v[242:245], v223 offset:4096
	s_waitcnt lgkmcnt(0)
	v_mfma_f32_16x16x32_bf16 v[242:245], v[84:87], v[242:245], 0
	s_mov_b32 s2, 0xe200000
	s_add_i32 s37, s37, s36
	s_add_i32 s38, s38, s39
	v_mfma_f32_16x16x32_bf16 v[242:245], v[92:95], v[246:249], v[242:245]
	ds_read_b128 v[246:249], v225 offset:4096
	v_lshl_add_u64 v[134:135], v[134:135], 0, s[30:31]
	v_readlane_b32 s73, v251, 9
	s_waitcnt lgkmcnt(0)
	v_mfma_f32_16x16x32_bf16 v[242:245], v[80:83], v[246:249], v[242:245]
	ds_read_b128 v[246:249], v226 offset:4096
	v_readlane_b32 s74, v251, 10
	v_readlane_b32 s75, v251, 11
	s_waitcnt lgkmcnt(0)
	v_mfma_f32_16x16x32_bf16 v[242:245], v[88:91], v[246:249], v[242:245]
	ds_read_b128 v[246:249], v224 offset:8192
	v_readlane_b32 s78, v251, 14
	v_readlane_b32 s79, v251, 15
	s_nop 4
	v_fma_f32 v236, v237, v242, v124
	v_fma_f32 v118, v238, v243, v125
	v_fma_f32 v117, v239, v244, v126
	v_fmac_f32_e32 v127, v240, v245
	ds_read_b128 v[242:245], v223 offset:8192
	s_waitcnt lgkmcnt(0)
	v_mfma_f32_16x16x32_bf16 v[242:245], v[84:87], v[242:245], 0
	v_readlane_b32 s80, v251, 16
	v_readlane_b32 s81, v251, 17
	v_readlane_b32 s82, v251, 18
	v_mfma_f32_16x16x32_bf16 v[242:245], v[92:95], v[246:249], v[242:245]
	ds_read_b128 v[246:249], v225 offset:8192
	v_readlane_b32 s83, v251, 19
	v_readlane_b32 s84, v251, 20
	s_waitcnt lgkmcnt(0)
	v_mfma_f32_16x16x32_bf16 v[242:245], v[80:83], v[246:249], v[242:245]
	ds_read_b128 v[246:249], v226 offset:8192
	v_readlane_b32 s85, v251, 21
	v_readlane_b32 s86, v251, 22
	s_waitcnt lgkmcnt(0)
	v_mfma_f32_16x16x32_bf16 v[242:245], v[88:91], v[246:249], v[242:245]
	ds_read_b128 v[246:249], v224 offset:12288
	v_readlane_b32 s87, v251, 23
	s_nop 5
	v_fma_f32 v125, v237, v242, v108
	v_fma_f32 v124, v238, v243, v109
	v_fma_f32 v108, v239, v244, v110
	v_fmac_f32_e32 v111, v240, v245
	ds_read_b128 v[242:245], v223 offset:12288
	s_waitcnt lgkmcnt(0)
	v_mfma_f32_16x16x32_bf16 v[242:245], v[84:87], v[242:245], 0
	v_mfma_f32_16x16x32_bf16 v[242:245], v[92:95], v[246:249], v[242:245]
	ds_read_b128 v[246:249], v225 offset:12288
	s_waitcnt lgkmcnt(0)
	v_mfma_f32_16x16x32_bf16 v[242:245], v[80:83], v[246:249], v[242:245]
	ds_read_b128 v[246:249], v226 offset:12288
	s_waitcnt lgkmcnt(0)
	v_mfma_f32_16x16x32_bf16 v[242:245], v[88:91], v[246:249], v[242:245]
	ds_read_b128 v[246:249], v224 offset:16384
	s_nop 6
	v_fma_f32 v126, v237, v242, v120
	v_fma_f32 v110, v238, v243, v121
	v_fma_f32 v109, v239, v244, v122
	v_fmac_f32_e32 v123, v240, v245
	ds_read_b128 v[242:245], v223 offset:16384
	s_waitcnt lgkmcnt(0)
	v_mfma_f32_16x16x32_bf16 v[242:245], v[84:87], v[242:245], 0
	v_mfma_f32_16x16x32_bf16 v[242:245], v[92:95], v[246:249], v[242:245]
	ds_read_b128 v[246:249], v225 offset:16384
	s_waitcnt lgkmcnt(0)
	v_mfma_f32_16x16x32_bf16 v[242:245], v[80:83], v[246:249], v[242:245]
	ds_read_b128 v[246:249], v226 offset:16384
	s_waitcnt lgkmcnt(0)
	v_mfma_f32_16x16x32_bf16 v[242:245], v[88:91], v[246:249], v[242:245]
	ds_read_b128 v[246:249], v224 offset:20480
	s_nop 6
	v_fma_f32 v121, v237, v242, v104
	v_fma_f32 v120, v238, v243, v105
	v_fma_f32 v104, v239, v244, v106
	v_fmac_f32_e32 v107, v240, v245
	ds_read_b128 v[242:245], v223 offset:20480
	s_waitcnt lgkmcnt(0)
	v_mfma_f32_16x16x32_bf16 v[242:245], v[84:87], v[242:245], 0
	v_mfma_f32_16x16x32_bf16 v[242:245], v[92:95], v[246:249], v[242:245]
	ds_read_b128 v[246:249], v225 offset:20480
	s_waitcnt lgkmcnt(0)
	v_mfma_f32_16x16x32_bf16 v[242:245], v[80:83], v[246:249], v[242:245]
	ds_read_b128 v[246:249], v226 offset:20480
	s_waitcnt lgkmcnt(0)
	v_mfma_f32_16x16x32_bf16 v[242:245], v[88:91], v[246:249], v[242:245]
	ds_read_b128 v[246:249], v224 offset:24576
	s_nop 6
	v_fma_f32 v112, v237, v242, v112
	v_fma_f32 v106, v238, v243, v113
	v_fma_f32 v105, v239, v244, v114
	v_fmac_f32_e32 v115, v240, v245
	ds_read_b128 v[242:245], v223 offset:24576
	s_waitcnt lgkmcnt(0)
	v_mfma_f32_16x16x32_bf16 v[242:245], v[84:87], v[242:245], 0
	v_mfma_f32_16x16x32_bf16 v[242:245], v[92:95], v[246:249], v[242:245]
	ds_read_b128 v[246:249], v225 offset:24576
	s_waitcnt lgkmcnt(0)
	v_mfma_f32_16x16x32_bf16 v[242:245], v[80:83], v[246:249], v[242:245]
	ds_read_b128 v[246:249], v226 offset:24576
	s_waitcnt lgkmcnt(0)
	v_mfma_f32_16x16x32_bf16 v[242:245], v[88:91], v[246:249], v[242:245]
	s_nop 7
	v_fma_f32 v113, v237, v242, v96
	v_fma_f32 v97, v238, v243, v97
	v_fma_f32 v96, v239, v244, v98
	v_fmac_f32_e32 v99, v240, v245
	ds_read_b128 v[242:245], v223 offset:28672
	s_waitcnt lgkmcnt(0)
	v_mfma_f32_16x16x32_bf16 v[84:87], v[84:87], v[242:245], 0
	ds_read_b128 v[242:245], v224 offset:28672
	s_waitcnt lgkmcnt(0)
	v_mfma_f32_16x16x32_bf16 v[84:87], v[92:95], v[242:245], v[84:87]
	ds_read_b128 v[92:95], v225 offset:28672
	s_waitcnt lgkmcnt(0)
	v_mfma_f32_16x16x32_bf16 v[80:83], v[80:83], v[92:95], v[84:87]
	s_nop 4
	ds_read_b128 v[84:87], v226 offset:28672
	s_waitcnt lgkmcnt(0)
	v_mfma_f32_16x16x32_bf16 v[80:83], v[88:91], v[84:87], v[80:83]
	v_and_b32_e32 v89, 64, v234
	v_xor_b32_e32 v88, 1, v234
	v_add_u32_e32 v95, 64, v89
	v_cmp_lt_i32_e32 vcc, v88, v95
	s_nop 3
	v_fma_f32 v94, v237, v80, v100
	v_lshlrev_b32_e32 v80, 2, v144
	v_cndmask_b32_e32 v88, v234, v88, vcc
	v_lshlrev_b32_e32 v91, 2, v88
	v_xor_b32_e32 v88, 2, v234
	v_cmp_lt_i32_e32 vcc, v88, v95
	v_lshl_or_b32 v80, s41, 9, v80
	v_fma_f32 v93, v238, v81, v101
	v_cndmask_b32_e32 v88, v234, v88, vcc
	v_lshlrev_b32_e32 v90, 2, v88
	v_xor_b32_e32 v88, 4, v234
	v_cmp_lt_i32_e32 vcc, v88, v95
	v_fma_f32 v92, v239, v82, v102
	v_fmac_f32_e32 v103, v240, v83
	global_load_dword v87, v80, s[76:77]
	global_load_dword v86, v80, s[76:77] offset:64
	global_load_dword v85, v80, s[76:77] offset:128
	global_load_dword v84, v80, s[76:77] offset:192
	global_load_dword v83, v80, s[76:77] offset:256
	global_load_dword v82, v80, s[76:77] offset:320
	global_load_dword v81, v80, s[76:77] offset:384
	s_nop 0
	global_load_dword v80, v80, s[76:77] offset:448
	v_cndmask_b32_e32 v88, v234, v88, vcc
	v_lshlrev_b32_e32 v89, 2, v88
	v_xor_b32_e32 v88, 8, v234
	v_cmp_lt_i32_e32 vcc, v88, v95
	v_add_f32_e32 v95, 0, v235
	v_add_f32_e32 v95, v95, v236
	v_add_f32_e32 v95, v95, v125
	v_add_f32_e32 v95, v95, v126
	v_add_f32_e32 v95, v95, v121
	v_add_f32_e32 v95, v95, v112
	v_add_f32_e32 v95, v95, v113
	v_add_f32_e32 v95, v95, v94
	s_nop 1
	v_cndmask_b32_e32 v88, v234, v88, vcc
	v_lshlrev_b32_e32 v88, 2, v88
	s_waitcnt lgkmcnt(0)
	v_add_f32_dpp v95, v95, v95 quad_perm:[1,0,3,2] row_mask:0xf bank_mask:0xf
	s_nop 1
	s_waitcnt lgkmcnt(0)
	v_add_f32_dpp v95, v95, v95 quad_perm:[2,3,0,1] row_mask:0xf bank_mask:0xf
	s_nop 1
	s_waitcnt lgkmcnt(0)
	v_add_f32_dpp v95, v95, v95 row_half_mirror row_mask:0xf bank_mask:0xf
	s_nop 1
	s_waitcnt lgkmcnt(0)
	v_add_f32_dpp v95, v95, v95 row_mirror row_mask:0xf bank_mask:0xf
	v_fmac_f32_e32 v236, 0xbc000000, v95
	v_fmac_f32_e32 v235, 0xbc000000, v95
	v_mul_f32_e32 v98, v236, v236
	v_fmac_f32_e32 v98, v235, v235
	v_fmac_f32_e32 v125, 0xbc000000, v95
	v_fmac_f32_e32 v98, v125, v125
	v_fmac_f32_e32 v126, 0xbc000000, v95
	v_fmac_f32_e32 v98, v126, v126
	v_fmac_f32_e32 v121, 0xbc000000, v95
	v_fmac_f32_e32 v98, v121, v121
	v_fmac_f32_e32 v112, 0xbc000000, v95
	v_fmac_f32_e32 v98, v112, v112
	v_fmac_f32_e32 v113, 0xbc000000, v95
	v_fmac_f32_e32 v98, v113, v113
	v_fmac_f32_e32 v94, 0xbc000000, v95
	v_fmac_f32_e32 v98, v94, v94
	s_nop 1
	s_waitcnt lgkmcnt(0)
	v_add_f32_dpp v95, v98, v98 quad_perm:[1,0,3,2] row_mask:0xf bank_mask:0xf
	s_nop 1
	s_waitcnt lgkmcnt(0)
	v_add_f32_dpp v95, v95, v95 quad_perm:[2,3,0,1] row_mask:0xf bank_mask:0xf
	s_nop 1
	s_waitcnt lgkmcnt(0)
	v_add_f32_dpp v95, v95, v95 row_half_mirror row_mask:0xf bank_mask:0xf
	s_nop 1
	s_waitcnt lgkmcnt(0)
	v_add_f32_dpp v95, v95, v95 row_mirror row_mask:0xf bank_mask:0xf
	v_fmamk_f32 v95, v95, 0x3c000000, v227
	v_rsq_f32_e32 v95, v95
	s_nop 0
	v_mul_f32_e32 v98, v235, v95
	s_waitcnt vmcnt(7)
	v_mul_f32_e32 v98, v87, v98
	v_cvt_pk_bf16_f32 v98, v98, v131
	ds_write_b16 v185, v98
	v_mul_f32_e32 v98, v236, v95
	s_waitcnt vmcnt(6)
	v_mul_f32_e32 v98, v86, v98
	v_cvt_pk_bf16_f32 v98, v98, v131
	ds_write_b16 v185, v98 offset:32
	v_mul_f32_e32 v98, v125, v95
	s_waitcnt vmcnt(5)
	v_mul_f32_e32 v98, v85, v98
	v_cvt_pk_bf16_f32 v98, v98, v131
	ds_write_b16 v185, v98 offset:64
	v_mul_f32_e32 v98, v126, v95
	s_waitcnt vmcnt(4)
	v_mul_f32_e32 v98, v84, v98
	v_cvt_pk_bf16_f32 v98, v98, v131
	ds_write_b16 v185, v98 offset:96
	v_mul_f32_e32 v98, v121, v95
	s_waitcnt vmcnt(3)
	v_mul_f32_e32 v98, v83, v98
	v_cvt_pk_bf16_f32 v98, v98, v131
	ds_write_b16 v185, v98 offset:128
	v_mul_f32_e32 v98, v112, v95
	s_waitcnt vmcnt(2)
	v_mul_f32_e32 v98, v82, v98
	v_cvt_pk_bf16_f32 v98, v98, v131
	ds_write_b16 v185, v98 offset:160
	v_mul_f32_e32 v98, v113, v95
	v_mul_f32_e32 v94, v94, v95
	s_waitcnt vmcnt(1)
	v_mul_f32_e32 v98, v81, v98
	s_waitcnt vmcnt(0)
	v_mul_f32_e32 v94, v80, v94
	v_cvt_pk_bf16_f32 v98, v98, v131
	ds_write_b16 v185, v98 offset:192
	v_cvt_pk_bf16_f32 v94, v94, v131
	ds_write_b16 v185, v94 offset:224
	v_add_f32_e32 v94, 0, v143
	v_add_f32_e32 v94, v94, v118
	v_add_f32_e32 v94, v94, v124
	v_add_f32_e32 v94, v94, v110
	v_add_f32_e32 v94, v94, v120
	v_add_f32_e32 v94, v94, v106
	v_add_f32_e32 v94, v94, v97
	v_add_f32_e32 v94, v94, v93
	s_nop 1
	s_waitcnt lgkmcnt(0)
	v_add_f32_dpp v94, v94, v94 quad_perm:[1,0,3,2] row_mask:0xf bank_mask:0xf
	s_nop 1
	s_waitcnt lgkmcnt(0)
	v_add_f32_dpp v94, v94, v94 quad_perm:[2,3,0,1] row_mask:0xf bank_mask:0xf
	s_nop 1
	s_waitcnt lgkmcnt(0)
	v_add_f32_dpp v94, v94, v94 row_half_mirror row_mask:0xf bank_mask:0xf
	s_nop 1
	s_waitcnt lgkmcnt(0)
	v_add_f32_dpp v94, v94, v94 row_mirror row_mask:0xf bank_mask:0xf
	v_fmac_f32_e32 v118, 0xbc000000, v94
	v_fmac_f32_e32 v143, 0xbc000000, v94
	v_mul_f32_e32 v95, v118, v118
	v_fmac_f32_e32 v95, v143, v143
	v_fmac_f32_e32 v124, 0xbc000000, v94
	v_fmac_f32_e32 v95, v124, v124
	v_fmac_f32_e32 v110, 0xbc000000, v94
	v_fmac_f32_e32 v95, v110, v110
	v_fmac_f32_e32 v120, 0xbc000000, v94
	v_fmac_f32_e32 v95, v120, v120
	v_fmac_f32_e32 v106, 0xbc000000, v94
	v_fmac_f32_e32 v95, v106, v106
	v_fmac_f32_e32 v97, 0xbc000000, v94
	v_fmac_f32_e32 v95, v97, v97
	v_fmac_f32_e32 v93, 0xbc000000, v94
	v_fmac_f32_e32 v95, v93, v93
	s_nop 1
	s_waitcnt lgkmcnt(0)
	v_add_f32_dpp v94, v95, v95 quad_perm:[1,0,3,2] row_mask:0xf bank_mask:0xf
	s_nop 1
	s_waitcnt lgkmcnt(0)
	v_add_f32_dpp v94, v94, v94 quad_perm:[2,3,0,1] row_mask:0xf bank_mask:0xf
	s_nop 1
	s_waitcnt lgkmcnt(0)
	v_add_f32_dpp v94, v94, v94 row_half_mirror row_mask:0xf bank_mask:0xf
	s_nop 1
	s_waitcnt lgkmcnt(0)
	v_add_f32_dpp v94, v94, v94 row_mirror row_mask:0xf bank_mask:0xf
	v_fmamk_f32 v94, v94, 0x3c000000, v227
	v_rsq_f32_e32 v94, v94
	s_nop 0
	v_mul_f32_e32 v95, v143, v94
	v_mul_f32_e32 v95, v87, v95
	v_cvt_pk_bf16_f32 v95, v95, v131
	ds_write_b16 v185, v95 offset:272
	v_mul_f32_e32 v95, v118, v94
	v_mul_f32_e32 v95, v86, v95
	v_cvt_pk_bf16_f32 v95, v95, v131
	ds_write_b16 v185, v95 offset:304
	v_mul_f32_e32 v95, v124, v94
	v_mul_f32_e32 v95, v85, v95
	v_cvt_pk_bf16_f32 v95, v95, v131
	ds_write_b16 v185, v95 offset:336
	v_mul_f32_e32 v95, v110, v94
	v_mul_f32_e32 v95, v84, v95
	v_cvt_pk_bf16_f32 v95, v95, v131
	ds_write_b16 v185, v95 offset:368
	v_mul_f32_e32 v95, v120, v94
	v_mul_f32_e32 v95, v83, v95
	v_cvt_pk_bf16_f32 v95, v95, v131
	ds_write_b16 v185, v95 offset:400
	v_mul_f32_e32 v95, v106, v94
	v_mul_f32_e32 v95, v82, v95
	v_cvt_pk_bf16_f32 v95, v95, v131
	ds_write_b16 v185, v95 offset:432
	v_mul_f32_e32 v95, v97, v94
	v_mul_f32_e32 v93, v93, v94
	v_mul_f32_e32 v95, v81, v95
	v_mul_f32_e32 v93, v80, v93
	v_cvt_pk_bf16_f32 v95, v95, v131
	ds_write_b16 v185, v95 offset:464
	v_cvt_pk_bf16_f32 v93, v93, v131
	ds_write_b16 v185, v93 offset:496
	v_add_f32_e32 v93, 0, v116
	v_add_f32_e32 v93, v93, v117
	v_add_f32_e32 v93, v93, v108
	v_add_f32_e32 v93, v93, v109
	v_add_f32_e32 v93, v93, v104
	v_add_f32_e32 v93, v93, v105
	v_add_f32_e32 v93, v93, v96
	v_add_f32_e32 v93, v93, v92
	s_nop 1
	s_waitcnt lgkmcnt(0)
	v_add_f32_dpp v93, v93, v93 quad_perm:[1,0,3,2] row_mask:0xf bank_mask:0xf
	s_nop 1
	s_waitcnt lgkmcnt(0)
	v_add_f32_dpp v93, v93, v93 quad_perm:[2,3,0,1] row_mask:0xf bank_mask:0xf
	s_nop 1
	s_waitcnt lgkmcnt(0)
	v_add_f32_dpp v93, v93, v93 row_half_mirror row_mask:0xf bank_mask:0xf
	s_nop 1
	s_waitcnt lgkmcnt(0)
	v_add_f32_dpp v93, v93, v93 row_mirror row_mask:0xf bank_mask:0xf
	v_fmac_f32_e32 v117, 0xbc000000, v93
	v_fmac_f32_e32 v116, 0xbc000000, v93
	v_mul_f32_e32 v94, v117, v117
	v_fmac_f32_e32 v94, v116, v116
	v_fmac_f32_e32 v108, 0xbc000000, v93
	v_fmac_f32_e32 v94, v108, v108
	v_fmac_f32_e32 v109, 0xbc000000, v93
	v_fmac_f32_e32 v94, v109, v109
	v_fmac_f32_e32 v104, 0xbc000000, v93
	v_fmac_f32_e32 v94, v104, v104
	v_fmac_f32_e32 v105, 0xbc000000, v93
	v_fmac_f32_e32 v94, v105, v105
	v_fmac_f32_e32 v96, 0xbc000000, v93
	v_fmac_f32_e32 v94, v96, v96
	v_fmac_f32_e32 v92, 0xbc000000, v93
	v_fmac_f32_e32 v94, v92, v92
	s_nop 1
	s_waitcnt lgkmcnt(0)
	v_add_f32_dpp v93, v94, v94 quad_perm:[1,0,3,2] row_mask:0xf bank_mask:0xf
	s_nop 1
	s_waitcnt lgkmcnt(0)
	v_add_f32_dpp v93, v93, v93 quad_perm:[2,3,0,1] row_mask:0xf bank_mask:0xf
	s_nop 1
	s_waitcnt lgkmcnt(0)
	v_add_f32_dpp v93, v93, v93 row_half_mirror row_mask:0xf bank_mask:0xf
	s_nop 1
	s_waitcnt lgkmcnt(0)
	v_add_f32_dpp v93, v93, v93 row_mirror row_mask:0xf bank_mask:0xf
	v_fmamk_f32 v93, v93, 0x3c000000, v227
	v_rsq_f32_e32 v93, v93
	s_nop 0
	v_mul_f32_e32 v94, v116, v93
	v_mul_f32_e32 v94, v87, v94
	v_cvt_pk_bf16_f32 v94, v94, v131
	ds_write_b16 v185, v94 offset:544
	v_mul_f32_e32 v94, v117, v93
	v_mul_f32_e32 v94, v86, v94
	v_cvt_pk_bf16_f32 v94, v94, v131
	ds_write_b16 v185, v94 offset:576
	v_mul_f32_e32 v94, v108, v93
	v_mul_f32_e32 v94, v85, v94
	v_cvt_pk_bf16_f32 v94, v94, v131
	ds_write_b16 v185, v94 offset:608
	v_mul_f32_e32 v94, v109, v93
	v_mul_f32_e32 v94, v84, v94
	v_cvt_pk_bf16_f32 v94, v94, v131
	ds_write_b16 v185, v94 offset:640
	v_mul_f32_e32 v94, v104, v93
	v_mul_f32_e32 v94, v83, v94
	v_cvt_pk_bf16_f32 v94, v94, v131
	ds_write_b16 v185, v94 offset:672
	v_mul_f32_e32 v94, v105, v93
	v_mul_f32_e32 v94, v82, v94
	v_cvt_pk_bf16_f32 v94, v94, v131
	ds_write_b16 v185, v94 offset:704
	v_mul_f32_e32 v94, v96, v93
	v_mul_f32_e32 v92, v92, v93
	v_mul_f32_e32 v94, v81, v94
	v_mul_f32_e32 v92, v80, v92
	v_cvt_pk_bf16_f32 v94, v94, v131
	ds_write_b16 v185, v94 offset:736
	v_cvt_pk_bf16_f32 v92, v92, v131
	ds_write_b16 v185, v92 offset:768
	v_add_f32_e32 v92, 0, v119
	v_add_f32_e32 v92, v92, v127
	v_add_f32_e32 v92, v92, v111
	v_add_f32_e32 v92, v92, v123
	v_add_f32_e32 v92, v92, v107
	v_add_f32_e32 v92, v92, v115
	v_add_f32_e32 v92, v92, v99
	v_add_f32_e32 v92, v92, v103
	s_nop 1
	s_waitcnt lgkmcnt(0)
	v_add_f32_dpp v92, v92, v92 quad_perm:[1,0,3,2] row_mask:0xf bank_mask:0xf
	s_nop 1
	s_waitcnt lgkmcnt(0)
	v_add_f32_dpp v92, v92, v92 quad_perm:[2,3,0,1] row_mask:0xf bank_mask:0xf
	s_nop 1
	s_waitcnt lgkmcnt(0)
	v_add_f32_dpp v92, v92, v92 row_half_mirror row_mask:0xf bank_mask:0xf
	s_nop 1
	s_waitcnt lgkmcnt(0)
	v_add_f32_dpp v92, v92, v92 row_mirror row_mask:0xf bank_mask:0xf
	v_fmac_f32_e32 v127, 0xbc000000, v92
	v_fmac_f32_e32 v119, 0xbc000000, v92
	v_mul_f32_e32 v93, v127, v127
	v_fmac_f32_e32 v93, v119, v119
	v_fmac_f32_e32 v111, 0xbc000000, v92
	v_fmac_f32_e32 v93, v111, v111
	v_fmac_f32_e32 v123, 0xbc000000, v92
	v_fmac_f32_e32 v93, v123, v123
	v_fmac_f32_e32 v107, 0xbc000000, v92
	v_fmac_f32_e32 v93, v107, v107
	v_fmac_f32_e32 v115, 0xbc000000, v92
	v_fmac_f32_e32 v93, v115, v115
	v_fmac_f32_e32 v99, 0xbc000000, v92
	v_fmac_f32_e32 v93, v99, v99
	v_fmac_f32_e32 v103, 0xbc000000, v92
	v_fmac_f32_e32 v93, v103, v103
	s_nop 1
	s_waitcnt lgkmcnt(0)
	v_add_f32_dpp v91, v93, v93 quad_perm:[1,0,3,2] row_mask:0xf bank_mask:0xf
	s_nop 1
	s_waitcnt lgkmcnt(0)
	v_add_f32_dpp v90, v91, v91 quad_perm:[2,3,0,1] row_mask:0xf bank_mask:0xf
	s_nop 1
	s_waitcnt lgkmcnt(0)
	v_add_f32_dpp v89, v90, v90 row_half_mirror row_mask:0xf bank_mask:0xf
	s_nop 1
	s_waitcnt lgkmcnt(0)
	v_add_f32_dpp v88, v89, v89 row_mirror row_mask:0xf bank_mask:0xf
	v_fmamk_f32 v88, v88, 0x3c000000, v227
	v_rsq_f32_e32 v88, v88
	s_nop 0
	v_mul_f32_e32 v89, v119, v88
	v_mul_f32_e32 v87, v87, v89
	v_cvt_pk_bf16_f32 v87, v87, v131
	ds_write_b16 v185, v87 offset:816
	v_mul_f32_e32 v87, v127, v88
	v_mul_f32_e32 v86, v86, v87
	v_cvt_pk_bf16_f32 v86, v86, v131
	ds_write_b16 v185, v86 offset:848
	v_mul_f32_e32 v86, v111, v88
	v_mul_f32_e32 v85, v85, v86
	v_cvt_pk_bf16_f32 v85, v85, v131
	ds_write_b16 v185, v85 offset:880
	v_mul_f32_e32 v85, v123, v88
	v_mul_f32_e32 v84, v84, v85
	v_cvt_pk_bf16_f32 v84, v84, v131
	ds_write_b16 v185, v84 offset:912
	v_mul_f32_e32 v84, v107, v88
	v_mul_f32_e32 v83, v83, v84
	v_cvt_pk_bf16_f32 v83, v83, v131
	ds_write_b16 v185, v83 offset:944
	v_mul_f32_e32 v83, v115, v88
	v_mul_f32_e32 v82, v82, v83
	v_cvt_pk_bf16_f32 v82, v82, v131
	ds_write_b16 v185, v82 offset:976
	v_mul_f32_e32 v82, v99, v88
	v_mul_f32_e32 v81, v81, v82
	v_cvt_pk_bf16_f32 v81, v81, v131
	ds_write_b16 v185, v81 offset:1008
	v_mul_f32_e32 v81, v103, v88
	v_lshlrev_b32_e32 v88, 16, v60
	v_mul_f32_e32 v90, 0xbfb8aa3b, v88
	v_exp_f32_e32 v90, v90
	v_mul_f32_e32 v80, v80, v81
	v_cvt_pk_bf16_f32 v80, v80, v131
	ds_write_b16 v185, v80 offset:1040
	s_waitcnt lgkmcnt(0)
	ds_read_b128 v[84:87], v228
	v_add_f32_e32 v90, 1.0, v90
	v_rcp_f32_e32 v90, v90
	v_and_b32_e32 v60, 0xffff0000, v60
	v_add_u32_e32 v80, s42, v179
	s_waitcnt lgkmcnt(0)
	v_lshlrev_b32_e32 v89, 16, v84
	v_mul_f32_e32 v88, v90, v88
	v_mul_f32_e32 v88, v88, v89
	v_mul_f32_e32 v89, 0xbfb8aa3b, v60
	v_exp_f32_e32 v89, v89
	v_and_b32_e32 v84, 0xffff0000, v84
	v_ashrrev_i32_e32 v81, 31, v80
	v_lshlrev_b64 v[80:81], 12, v[80:81]
	v_add_f32_e32 v89, 1.0, v89
	v_rcp_f32_e32 v89, v89
	v_lshl_add_u64 v[80:81], s[92:93], 0, v[80:81]
	v_lshl_add_u64 v[80:81], v[80:81], 0, s[46:47]
	v_lshl_add_u64 v[82:83], v[80:81], 0, v[130:131]
	v_mul_f32_e32 v60, v89, v60
	v_mul_f32_e32 v60, v60, v84
	v_lshlrev_b32_e32 v84, 16, v61
	v_mul_f32_e32 v89, 0xbfb8aa3b, v84
	v_exp_f32_e32 v89, v89
	v_cvt_pk_bf16_f32 v60, v88, v60
	v_and_b32_e32 v61, 0xffff0000, v61
	v_lshlrev_b32_e32 v88, 16, v85
	v_add_f32_e32 v89, 1.0, v89
	v_rcp_f32_e32 v89, v89
	v_and_b32_e32 v85, 0xffff0000, v85
	v_lshl_add_u64 v[80:81], v[82:83], 0, s[16:17]
	v_add_co_u32_e32 v82, vcc, s2, v82
	v_mul_f32_e32 v84, v89, v84
	v_mul_f32_e32 v84, v84, v88
	v_mul_f32_e32 v88, 0xbfb8aa3b, v61
	v_exp_f32_e32 v88, v88
	v_addc_co_u32_e32 v83, vcc, 0, v83, vcc
	s_andn2_b64 vcc, exec, s[34:35]
	v_add_f32_e32 v88, 1.0, v88
	v_rcp_f32_e32 v88, v88
	s_nop 0
	v_mul_f32_e32 v61, v88, v61
	v_mul_f32_e32 v61, v61, v85
	v_cvt_pk_bf16_f32 v61, v84, v61
	v_lshlrev_b32_e32 v84, 16, v62
	v_mul_f32_e32 v88, 0xbfb8aa3b, v84
	v_exp_f32_e32 v88, v88
	v_and_b32_e32 v62, 0xffff0000, v62
	v_lshlrev_b32_e32 v85, 16, v86
	v_add_f32_e32 v88, 1.0, v88
	v_rcp_f32_e32 v88, v88
	s_nop 0
	v_mul_f32_e32 v84, v88, v84
	v_mul_f32_e32 v84, v84, v85
	v_and_b32_e32 v85, 0xffff0000, v86
	v_mul_f32_e32 v86, 0xbfb8aa3b, v62
	v_exp_f32_e32 v86, v86
	s_nop 0
	v_add_f32_e32 v86, 1.0, v86
	v_rcp_f32_e32 v86, v86
	s_nop 0
	v_mul_f32_e32 v62, v86, v62
	v_mul_f32_e32 v62, v62, v85
	v_cvt_pk_bf16_f32 v62, v84, v62
	v_lshlrev_b32_e32 v84, 16, v63
	v_mul_f32_e32 v86, 0xbfb8aa3b, v84
	v_exp_f32_e32 v86, v86
	v_and_b32_e32 v63, 0xffff0000, v63
	v_lshlrev_b32_e32 v85, 16, v87
	v_add_f32_e32 v86, 1.0, v86
	v_rcp_f32_e32 v86, v86
	s_nop 0
	v_mul_f32_e32 v84, v86, v84
	v_mul_f32_e32 v86, 0xbfb8aa3b, v63
	v_exp_f32_e32 v86, v86
	v_mul_f32_e32 v84, v84, v85
	v_and_b32_e32 v85, 0xffff0000, v87
	v_add_f32_e32 v86, 1.0, v86
	v_rcp_f32_e32 v86, v86
	s_nop 0
	v_mul_f32_e32 v63, v86, v63
	v_mul_f32_e32 v63, v63, v85
	v_cvt_pk_bf16_f32 v63, v84, v63
	global_store_dwordx4 v[82:83], v[60:63], off offset:2048
	v_lshlrev_b32_e32 v82, 16, v56
	v_mul_f32_e32 v84, 0xbfb8aa3b, v82
	v_exp_f32_e32 v84, v84
	ds_read_b128 v[60:63], v228 offset:16
	v_and_b32_e32 v56, 0xffff0000, v56
	v_add_f32_e32 v84, 1.0, v84
	v_rcp_f32_e32 v84, v84
	s_waitcnt lgkmcnt(0)
	v_lshlrev_b32_e32 v83, 16, v60
	v_and_b32_e32 v60, 0xffff0000, v60
	v_mul_f32_e32 v82, v84, v82
	v_mul_f32_e32 v82, v82, v83
	v_mul_f32_e32 v83, 0xbfb8aa3b, v56
	v_exp_f32_e32 v83, v83
	s_nop 0
	v_add_f32_e32 v83, 1.0, v83
	v_rcp_f32_e32 v83, v83
	s_nop 0
	v_mul_f32_e32 v56, v83, v56
	v_mul_f32_e32 v56, v56, v60
	v_lshlrev_b32_e32 v60, 16, v57
	v_mul_f32_e32 v83, 0xbfb8aa3b, v60
	v_exp_f32_e32 v83, v83
	v_cvt_pk_bf16_f32 v56, v82, v56
	v_and_b32_e32 v57, 0xffff0000, v57
	v_lshlrev_b32_e32 v82, 16, v61
	v_add_f32_e32 v83, 1.0, v83
	v_rcp_f32_e32 v83, v83
	v_and_b32_e32 v61, 0xffff0000, v61
	v_mul_f32_e32 v60, v83, v60
	v_mul_f32_e32 v60, v60, v82
	v_mul_f32_e32 v82, 0xbfb8aa3b, v57
	v_exp_f32_e32 v82, v82
	s_nop 0
	v_add_f32_e32 v82, 1.0, v82
	v_rcp_f32_e32 v82, v82
	s_nop 0
	v_mul_f32_e32 v57, v82, v57
	v_mul_f32_e32 v57, v57, v61
	v_cvt_pk_bf16_f32 v57, v60, v57
	v_lshlrev_b32_e32 v60, 16, v58
	v_mul_f32_e32 v82, 0xbfb8aa3b, v60
	v_exp_f32_e32 v82, v82
	v_and_b32_e32 v58, 0xffff0000, v58
	v_lshlrev_b32_e32 v61, 16, v62
	v_add_f32_e32 v82, 1.0, v82
	v_rcp_f32_e32 v82, v82
	s_nop 0
	v_mul_f32_e32 v60, v82, v60
	v_mul_f32_e32 v60, v60, v61
	v_and_b32_e32 v61, 0xffff0000, v62
	v_mul_f32_e32 v62, 0xbfb8aa3b, v58
	v_exp_f32_e32 v62, v62
	s_nop 0
	v_add_f32_e32 v62, 1.0, v62
	v_rcp_f32_e32 v62, v62
	s_nop 0
	v_mul_f32_e32 v58, v62, v58
	v_mul_f32_e32 v58, v58, v61
	v_cvt_pk_bf16_f32 v58, v60, v58
	v_lshlrev_b32_e32 v60, 16, v59
	v_mul_f32_e32 v62, 0xbfb8aa3b, v60
	v_exp_f32_e32 v62, v62
	v_and_b32_e32 v59, 0xffff0000, v59
	v_lshlrev_b32_e32 v61, 16, v63
	v_add_f32_e32 v62, 1.0, v62
	v_rcp_f32_e32 v62, v62
	s_nop 0
	v_mul_f32_e32 v60, v62, v60
	v_mul_f32_e32 v62, 0xbfb8aa3b, v59
	v_exp_f32_e32 v62, v62
	v_mul_f32_e32 v60, v60, v61
	v_and_b32_e32 v61, 0xffff0000, v63
	v_mov_b32_e32 v63, v75
	v_add_f32_e32 v62, 1.0, v62
	v_rcp_f32_e32 v62, v62
	s_nop 0
	v_mul_f32_e32 v59, v62, v59
	v_mul_f32_e32 v59, v59, v61
	v_cvt_pk_bf16_f32 v59, v60, v59
	v_lshlrev_b32_e32 v60, 16, v52
	v_mul_f32_e32 v62, 0xbfb8aa3b, v60
	v_exp_f32_e32 v62, v62
	global_store_dwordx4 v[80:81], v[56:59], off offset:16
	ds_read_b128 v[56:59], v228 offset:32
	v_and_b32_e32 v52, 0xffff0000, v52
	v_add_f32_e32 v62, 1.0, v62
	v_rcp_f32_e32 v62, v62
	s_waitcnt lgkmcnt(0)
	v_lshlrev_b32_e32 v61, 16, v56
	v_and_b32_e32 v56, 0xffff0000, v56
	v_mul_f32_e32 v60, v62, v60
	v_mul_f32_e32 v60, v60, v61
	v_mul_f32_e32 v61, 0xbfb8aa3b, v52
	v_exp_f32_e32 v61, v61
	v_mov_b32_e32 v62, v74
	v_add_f32_e32 v61, 1.0, v61
	v_rcp_f32_e32 v61, v61
	s_nop 0
	v_mul_f32_e32 v52, v61, v52
	v_mul_f32_e32 v52, v52, v56
	v_lshlrev_b32_e32 v56, 16, v53
	v_mul_f32_e32 v61, 0xbfb8aa3b, v56
	v_exp_f32_e32 v61, v61
	v_cvt_pk_bf16_f32 v52, v60, v52
	v_and_b32_e32 v53, 0xffff0000, v53
	v_lshlrev_b32_e32 v60, 16, v57
	v_add_f32_e32 v61, 1.0, v61
	v_rcp_f32_e32 v61, v61
	v_and_b32_e32 v57, 0xffff0000, v57
	v_mul_f32_e32 v56, v61, v56
	v_mul_f32_e32 v56, v56, v60
	v_mul_f32_e32 v60, 0xbfb8aa3b, v53
	v_exp_f32_e32 v60, v60
	v_mov_b32_e32 v61, v73
	v_add_f32_e32 v60, 1.0, v60
	v_rcp_f32_e32 v60, v60
	s_nop 0
	v_mul_f32_e32 v53, v60, v53
	v_mul_f32_e32 v53, v53, v57
	v_cvt_pk_bf16_f32 v53, v56, v53
	v_lshlrev_b32_e32 v56, 16, v54
	v_mul_f32_e32 v60, 0xbfb8aa3b, v56
	v_exp_f32_e32 v60, v60
	v_and_b32_e32 v54, 0xffff0000, v54
	v_lshlrev_b32_e32 v57, 16, v58
	v_add_f32_e32 v60, 1.0, v60
	v_rcp_f32_e32 v60, v60
	s_nop 0
	v_mul_f32_e32 v56, v60, v56
	v_mul_f32_e32 v56, v56, v57
	v_and_b32_e32 v57, 0xffff0000, v58
	v_mul_f32_e32 v58, 0xbfb8aa3b, v54
	v_exp_f32_e32 v58, v58
	v_mov_b32_e32 v60, v72
	v_add_f32_e32 v58, 1.0, v58
	v_rcp_f32_e32 v58, v58
	s_nop 0
	v_mul_f32_e32 v54, v58, v54
	v_mul_f32_e32 v54, v54, v57
	v_cvt_pk_bf16_f32 v54, v56, v54
	v_lshlrev_b32_e32 v56, 16, v55
	v_mul_f32_e32 v58, 0xbfb8aa3b, v56
	v_exp_f32_e32 v58, v58
	v_and_b32_e32 v55, 0xffff0000, v55
	v_lshlrev_b32_e32 v57, 16, v59
	v_add_f32_e32 v58, 1.0, v58
	v_rcp_f32_e32 v58, v58
	s_nop 0
	v_mul_f32_e32 v56, v58, v56
	v_mul_f32_e32 v58, 0xbfb8aa3b, v55
	v_exp_f32_e32 v58, v58
	v_mul_f32_e32 v56, v56, v57
	v_and_b32_e32 v57, 0xffff0000, v59
	v_mov_b32_e32 v59, v67
	v_add_f32_e32 v58, 1.0, v58
	v_rcp_f32_e32 v58, v58
	s_nop 0
	v_mul_f32_e32 v55, v58, v55
	v_mul_f32_e32 v55, v55, v57
	v_cvt_pk_bf16_f32 v55, v56, v55
	v_lshlrev_b32_e32 v56, 16, v48
	v_mul_f32_e32 v58, 0xbfb8aa3b, v56
	v_exp_f32_e32 v58, v58
	global_store_dwordx4 v[80:81], v[52:55], off offset:32
	ds_read_b128 v[52:55], v228 offset:48
	v_and_b32_e32 v48, 0xffff0000, v48
	v_add_f32_e32 v58, 1.0, v58
	v_rcp_f32_e32 v58, v58
	s_waitcnt lgkmcnt(0)
	v_lshlrev_b32_e32 v57, 16, v52
	v_and_b32_e32 v52, 0xffff0000, v52
	v_mul_f32_e32 v56, v58, v56
	v_mul_f32_e32 v56, v56, v57
	v_mul_f32_e32 v57, 0xbfb8aa3b, v48
	v_exp_f32_e32 v57, v57
	v_mov_b32_e32 v58, v66
	v_add_f32_e32 v57, 1.0, v57
	v_rcp_f32_e32 v57, v57
	s_nop 0
	v_mul_f32_e32 v48, v57, v48
	v_mul_f32_e32 v48, v48, v52
	v_lshlrev_b32_e32 v52, 16, v49
	v_mul_f32_e32 v57, 0xbfb8aa3b, v52
	v_exp_f32_e32 v57, v57
	v_cvt_pk_bf16_f32 v48, v56, v48
	v_and_b32_e32 v49, 0xffff0000, v49
	v_lshlrev_b32_e32 v56, 16, v53
	v_add_f32_e32 v57, 1.0, v57
	v_rcp_f32_e32 v57, v57
	v_and_b32_e32 v53, 0xffff0000, v53
	v_mul_f32_e32 v52, v57, v52
	v_mul_f32_e32 v52, v52, v56
	v_mul_f32_e32 v56, 0xbfb8aa3b, v49
	v_exp_f32_e32 v56, v56
	v_mov_b32_e32 v57, v65
	v_add_f32_e32 v56, 1.0, v56
	v_rcp_f32_e32 v56, v56
	s_nop 0
	v_mul_f32_e32 v49, v56, v49
	v_mul_f32_e32 v49, v49, v53
	v_cvt_pk_bf16_f32 v49, v52, v49
	v_lshlrev_b32_e32 v52, 16, v50
	v_mul_f32_e32 v56, 0xbfb8aa3b, v52
	v_exp_f32_e32 v56, v56
	v_and_b32_e32 v50, 0xffff0000, v50
	v_lshlrev_b32_e32 v53, 16, v54
	v_add_f32_e32 v56, 1.0, v56
	v_rcp_f32_e32 v56, v56
	s_nop 0
	v_mul_f32_e32 v52, v56, v52
	v_mul_f32_e32 v52, v52, v53
	v_and_b32_e32 v53, 0xffff0000, v54
	v_mul_f32_e32 v54, 0xbfb8aa3b, v50
	v_exp_f32_e32 v54, v54
	v_mov_b32_e32 v56, v64
	v_add_f32_e32 v54, 1.0, v54
	v_rcp_f32_e32 v54, v54
	s_nop 0
	v_mul_f32_e32 v50, v54, v50
	v_mul_f32_e32 v50, v50, v53
	v_cvt_pk_bf16_f32 v50, v52, v50
	v_lshlrev_b32_e32 v52, 16, v51
	v_mul_f32_e32 v54, 0xbfb8aa3b, v52
	v_exp_f32_e32 v54, v54
	v_and_b32_e32 v51, 0xffff0000, v51
	v_lshlrev_b32_e32 v53, 16, v55
	v_add_f32_e32 v54, 1.0, v54
	v_rcp_f32_e32 v54, v54
	s_nop 0
	v_mul_f32_e32 v52, v54, v52
	v_mul_f32_e32 v54, 0xbfb8aa3b, v51
	v_exp_f32_e32 v54, v54
	v_mul_f32_e32 v52, v52, v53
	v_and_b32_e32 v53, 0xffff0000, v55
	v_mov_b32_e32 v55, v71
	v_add_f32_e32 v54, 1.0, v54
	v_rcp_f32_e32 v54, v54
	s_nop 0
	v_mul_f32_e32 v51, v54, v51
	v_mul_f32_e32 v51, v51, v53
	v_cvt_pk_bf16_f32 v51, v52, v51
	global_store_dwordx4 v[80:81], v[48:51], off offset:48
	v_mov_b32_e32 v52, v68
	v_mov_b32_e32 v53, v69
	v_mov_b32_e32 v54, v70
	v_mov_b32_e32 v48, v76
	v_mov_b32_e32 v49, v77
	v_mov_b32_e32 v50, v78
	v_mov_b32_e32 v51, v79
	s_barrier
	s_cbranch_vccz .LBB0_436
